# dense attention peeled steps 59-62: row-max tree and rescale decision skipped under the same score-bound guard
# speedup vs baseline: 1.0434x; 1.0243x over previous
.LBB0_401:
	ds_read_b64_tr_b16 v[176:177], v224 offset:32768
	ds_read_b64_tr_b16 v[178:179], v224 offset:33280
	s_waitcnt lgkmcnt(9)
	v_mfma_f32_32x32x16_bf16 v[96:111], v[80:83], v[156:159], v[32:47]
	v_add_f32_e32 v84, v64, v65
	v_add_f32_e32 v84, v66, v84
	v_add_f32_e32 v84, v67, v84
	v_add_f32_e32 v84, v68, v84
	v_add_f32_e32 v84, v69, v84
	v_cvt_pk_bf16_f32 v148, v64, v65
	v_cvt_pk_bf16_f32 v149, v66, v67
	ds_read_b64_tr_b16 v[172:173], v224 offset:36864
	ds_read_b64_tr_b16 v[174:175], v224 offset:37376
	v_add_f32_e32 v64, v70, v84
	s_waitcnt lgkmcnt(10)
	v_mfma_f32_32x32x16_bf16 v[80:95], v[164:167], v[156:159], v[32:47]
	v_add_f32_e32 v64, v71, v64
	v_add_f32_e32 v64, v72, v64
	v_add_f32_e32 v128, v73, v64
	v_cvt_pk_bf16_f32 v150, v68, v69
	v_cvt_pk_bf16_f32 v151, v70, v71
	ds_read_b64_tr_b16 v[64:65], v224 offset:33792
	ds_read_b64_tr_b16 v[66:67], v224 offset:34304
	s_waitcnt lgkmcnt(11)
	v_mfma_f32_32x32x16_bf16 v[96:111], v[168:171], v[152:155], v[96:111]
	v_add_f32_e32 v68, v74, v128
	v_add_f32_e32 v68, v75, v68
	v_add_f32_e32 v68, v76, v68
	v_add_f32_e32 v128, v77, v68
	v_cvt_pk_bf16_f32 v144, v72, v73
	v_cvt_pk_bf16_f32 v145, v74, v75
	ds_read_b64_tr_b16 v[68:69], v224 offset:37888
	ds_read_b64_tr_b16 v[70:71], v224 offset:38400
	s_waitcnt lgkmcnt(12)
	v_mfma_f32_32x32x16_bf16 v[80:95], v[160:163], v[152:155], v[80:95]
	v_add_f32_e32 v72, v78, v128
	v_add_f32_e32 v72, v79, v72
	v_add_f32_e32 v72, v48, v72
	v_add_f32_e32 v128, v49, v72
	v_cvt_pk_bf16_f32 v146, v76, v77
	v_cvt_pk_bf16_f32 v147, v78, v79
	ds_read_b64_tr_b16 v[72:73], v224 offset:34816
	ds_read_b64_tr_b16 v[74:75], v224 offset:35328
	s_waitcnt lgkmcnt(13)
	v_mfma_f32_32x32x16_bf16 v[96:111], v[124:127], v[140:143], v[96:111]
	v_add_f32_e32 v76, v50, v128
	v_add_f32_e32 v76, v51, v76
	v_add_f32_e32 v76, v52, v76
	v_add_f32_e32 v76, v53, v76
	v_cvt_pk_bf16_f32 v136, v48, v49
	v_cvt_pk_bf16_f32 v137, v50, v51
	ds_read_b64_tr_b16 v[48:49], v224 offset:38912
	ds_read_b64_tr_b16 v[50:51], v224 offset:39424
	s_waitcnt lgkmcnt(14)
	v_mfma_f32_32x32x16_bf16 v[80:95], v[120:123], v[140:143], v[80:95]
	v_add_f32_e32 v76, v54, v76
	v_add_f32_e32 v76, v55, v76
	v_add_f32_e32 v76, v56, v76
	v_add_f32_e32 v76, v57, v76
	v_cvt_pk_bf16_f32 v138, v52, v53
	v_cvt_pk_bf16_f32 v139, v54, v55
	ds_read_b64_tr_b16 v[52:53], v224 offset:35840
	ds_read_b64_tr_b16 v[54:55], v224 offset:36352
	s_waitcnt lgkmcnt(14)
	v_mfma_f32_32x32x16_bf16 v[96:111], v[116:119], v[132:135], v[96:111]
	v_add_f32_e32 v76, v58, v76
	v_add_f32_e32 v76, v59, v76
	v_add_f32_e32 v76, v60, v76
	v_add_f32_e32 v76, v61, v76
	v_cvt_pk_bf16_f32 v128, v56, v57
	v_cvt_pk_bf16_f32 v129, v58, v59
	ds_read_b64_tr_b16 v[56:57], v224 offset:39936
	ds_read_b64_tr_b16 v[58:59], v224 offset:40448
	v_mfma_f32_32x32x16_bf16 v[80:95], v[112:115], v[132:135], v[80:95]
	v_add_f32_e32 v76, v62, v76
	v_add_f32_e32 v76, v63, v76
	v_add_f32_e32 v76, 0, v76
	v_cvt_pk_bf16_f32 v130, v60, v61
	v_cvt_pk_bf16_f32 v131, v62, v63
	s_mov_b64 s[20:21], 0x7c000
	s_cmp_lg_u32 0, -1
	v_lshl_add_u64 v[60:61], v[204:205], 0, s[20:21]
	s_cselect_b32 s20, 0, 0
	s_add_i32 s20, s20, s38
	s_addk_i32 s20, 0x4000
	s_mov_b32 s21, m0
	s_mov_b32 m0, s20
	s_nop 0
	global_load_lds_dwordx4 v[60:61], off
	s_mov_b32 m0, s21
	s_mov_b64 s[20:21], 0x78000
	v_lshl_add_u64 v[60:61], v[202:203], 0, s[20:21]
	s_mov_b32 s20, m0
	s_mov_b32 m0, s35
	s_nop 0
	global_load_lds_dwordx4 v[60:61], off
	s_mov_b32 m0, s20
	s_cmp_lg_u32 s101, 0
	s_cbranch_scc0 .Ltailmx_0
	v_add_f32_e32 v188, v184, v76
	s_mov_b64 s[20:21], 0
	s_branch .LBB0_402
.Ltailmx_0:
	v_max_f32_e32 v60, v97, v97
	v_max_f32_e32 v61, v96, v96
	v_max_f32_e32 v60, v61, v60
	v_max3_f32 v61, v98, v99, v81
	v_max3_f32 v60, v60, v80, v82
	v_max3_f32 v60, v60, v83, v100
	v_max3_f32 v61, v61, v102, v103
	v_max3_f32 v60, v60, v101, v84
	v_max3_f32 v61, v61, v86, v87
	v_max3_f32 v60, v60, v85, v104
	v_max3_f32 v61, v61, v106, v107
	v_max3_f32 v60, v60, v105, v88
	v_max3_f32 v61, v61, v90, v91
	v_max3_f32 v60, v60, v89, v108
	v_max3_f32 v61, v61, v110, v111
	v_max3_f32 v60, v60, v109, v92
	v_max3_f32 v61, v61, v94, v95
	v_max3_f32 v60, v60, v93, v61
	v_mov_b32_e32 v61, v60
	s_nop 1
	v_permlane32_swap_b32_e32 v60, v61
	v_max_f32_e32 v61, v61, v61
	v_max_f32_e32 v60, v60, v60
	v_max_f32_e32 v60, v60, v61
	v_cmp_lt_f32_e32 vcc, s1, v60
	s_cmp_lg_u64 vcc, 0
	v_add_f32_e32 v188, v184, v76
	s_cselect_b64 s[20:21], -1, 0
	s_cbranch_vccnz .LBB0_418

.LBB0_404:
	ds_read_b64_tr_b16 v[160:161], v224 offset:40960
	ds_read_b64_tr_b16 v[162:163], v224 offset:41472
	s_waitcnt lgkmcnt(9)
	v_mfma_f32_32x32x16_bf16 v[112:127], v[60:63], v[156:159], v[32:47]
	v_add_f32_e32 v48, v96, v97
	v_add_f32_e32 v48, v98, v48
	v_add_f32_e32 v48, v99, v48
	v_add_f32_e32 v48, v100, v48
	v_add_f32_e32 v48, v101, v48
	v_cvt_pk_bf16_f32 v148, v96, v97
	v_cvt_pk_bf16_f32 v149, v98, v99
	ds_read_b64_tr_b16 v[72:73], v224 offset:45056
	ds_read_b64_tr_b16 v[74:75], v224 offset:45568
	v_add_f32_e32 v48, v102, v48
	v_add_f32_e32 v48, v103, v48
	v_add_f32_e32 v48, v104, v48
	v_add_f32_e32 v68, v105, v48
	s_waitcnt lgkmcnt(10)
	v_mfma_f32_32x32x16_bf16 v[48:63], v[180:183], v[156:159], v[32:47]
	v_cvt_pk_bf16_f32 v150, v100, v101
	v_cvt_pk_bf16_f32 v151, v102, v103
	ds_read_b64_tr_b16 v[64:65], v224 offset:41984
	ds_read_b64_tr_b16 v[66:67], v224 offset:42496
	s_waitcnt lgkmcnt(11)
	v_mfma_f32_32x32x16_bf16 v[112:127], v[184:187], v[152:155], v[112:127]
	v_add_f32_e32 v68, v106, v68
	v_add_f32_e32 v68, v107, v68
	v_add_f32_e32 v68, v108, v68
	v_add_f32_e32 v96, v109, v68
	v_cvt_pk_bf16_f32 v144, v104, v105
	v_cvt_pk_bf16_f32 v145, v106, v107
	ds_read_b64_tr_b16 v[68:69], v224 offset:46080
	ds_read_b64_tr_b16 v[70:71], v224 offset:46592
	s_waitcnt lgkmcnt(12)
	v_mfma_f32_32x32x16_bf16 v[48:63], v[76:79], v[152:155], v[48:63]
	v_add_f32_e32 v76, v110, v96
	v_add_f32_e32 v76, v111, v76
	v_add_f32_e32 v76, v80, v76
	v_add_f32_e32 v96, v81, v76
	v_cvt_pk_bf16_f32 v146, v108, v109
	v_cvt_pk_bf16_f32 v147, v110, v111
	ds_read_b64_tr_b16 v[76:77], v224 offset:43008
	ds_read_b64_tr_b16 v[78:79], v224 offset:43520
	s_waitcnt lgkmcnt(13)
	v_mfma_f32_32x32x16_bf16 v[112:127], v[176:179], v[140:143], v[112:127]
	v_add_f32_e32 v96, v82, v96
	v_add_f32_e32 v96, v83, v96
	v_add_f32_e32 v96, v84, v96
	v_add_f32_e32 v96, v85, v96
	v_cvt_pk_bf16_f32 v136, v80, v81
	v_cvt_pk_bf16_f32 v137, v82, v83
	ds_read_b64_tr_b16 v[80:81], v224 offset:47104
	ds_read_b64_tr_b16 v[82:83], v224 offset:47616
	s_waitcnt lgkmcnt(14)
	v_mfma_f32_32x32x16_bf16 v[48:63], v[172:175], v[140:143], v[48:63]
	v_add_f32_e32 v96, v86, v96
	v_add_f32_e32 v96, v87, v96
	v_add_f32_e32 v96, v88, v96
	v_add_f32_e32 v96, v89, v96
	v_cvt_pk_bf16_f32 v138, v84, v85
	v_cvt_pk_bf16_f32 v139, v86, v87
	ds_read_b64_tr_b16 v[84:85], v224 offset:44032
	ds_read_b64_tr_b16 v[86:87], v224 offset:44544
	s_waitcnt lgkmcnt(14)
	v_mfma_f32_32x32x16_bf16 v[112:127], v[168:171], v[132:135], v[112:127]
	v_add_f32_e32 v96, v90, v96
	v_add_f32_e32 v96, v91, v96
	v_add_f32_e32 v96, v92, v96
	v_add_f32_e32 v96, v93, v96
	v_cvt_pk_bf16_f32 v128, v88, v89
	v_cvt_pk_bf16_f32 v129, v90, v91
	ds_read_b64_tr_b16 v[88:89], v224 offset:48128
	ds_read_b64_tr_b16 v[90:91], v224 offset:48640
	v_mfma_f32_32x32x16_bf16 v[48:63], v[164:167], v[132:135], v[48:63]
	v_add_f32_e32 v96, v94, v96
	v_add_f32_e32 v96, v95, v96
	v_add_f32_e32 v96, 0, v96
	v_cvt_pk_bf16_f32 v130, v92, v93
	v_cvt_pk_bf16_f32 v131, v94, v95
	s_mov_b64 s[20:21], 0x7e000
	v_lshl_add_u64 v[92:93], v[204:205], 0, s[20:21]
	s_mov_b32 s20, m0
	s_mov_b32 m0, s39
	s_nop 0
	global_load_lds_dwordx4 v[92:93], off
	s_mov_b32 m0, s20
	s_mov_b64 s[20:21], 0x7a000
	s_cmp_lg_u32 0, -1
	v_lshl_add_u64 v[92:93], v[202:203], 0, s[20:21]
	s_cselect_b32 s20, 0, 0
	s_add_i32 s20, s20, s38
	s_add_i32 s20, s20, 0x8000
	s_mov_b32 s21, m0
	s_mov_b32 m0, s20
	s_nop 0
	global_load_lds_dwordx4 v[92:93], off
	s_mov_b32 m0, s21
	s_cmp_lg_u32 s101, 0
	s_cbranch_scc0 .Ltailmx_1
	v_add_f32_e32 v188, v188, v96
	s_mov_b64 s[20:21], 0
	s_branch .LBB0_405
.Ltailmx_1:
	v_max_f32_e32 v92, v113, v113
	v_max_f32_e32 v93, v112, v112
	v_max_f32_e32 v92, v93, v92
	v_max3_f32 v93, v114, v115, v49
	v_max3_f32 v92, v92, v48, v50
	v_max3_f32 v92, v92, v51, v116
	v_max3_f32 v93, v93, v118, v119
	v_max3_f32 v92, v92, v117, v52
	v_max3_f32 v93, v93, v54, v55
	v_max3_f32 v92, v92, v53, v120
	v_max3_f32 v93, v93, v122, v123
	v_max3_f32 v92, v92, v121, v56
	v_max3_f32 v93, v93, v58, v59
	v_max3_f32 v92, v92, v57, v124
	v_max3_f32 v93, v93, v126, v127
	v_max3_f32 v92, v92, v125, v60
	v_max3_f32 v93, v93, v62, v63
	v_max3_f32 v92, v92, v61, v93
	v_mov_b32_e32 v93, v92
	s_nop 1
	v_permlane32_swap_b32_e32 v92, v93
	v_max_f32_e32 v93, v93, v93
	v_max_f32_e32 v92, v92, v92
	v_max_f32_e32 v92, v92, v93
	v_cmp_lt_f32_e32 vcc, s1, v92
	s_cmp_lg_u64 vcc, 0
	v_add_f32_e32 v188, v188, v96
	s_cselect_b64 s[20:21], -1, 0
	s_cbranch_vccnz .LBB0_421

.LBB0_407:
	ds_read_b64_tr_b16 v[160:161], v224 offset:24576
	ds_read_b64_tr_b16 v[162:163], v224 offset:25088
	s_waitcnt lgkmcnt(9)
	v_mfma_f32_32x32x16_bf16 v[96:111], v[72:75], v[156:159], v[32:47]
	v_add_f32_e32 v64, v112, v113
	v_add_f32_e32 v64, v114, v64
	v_add_f32_e32 v64, v115, v64
	v_add_f32_e32 v64, v116, v64
	v_add_f32_e32 v64, v117, v64
	v_cvt_pk_bf16_f32 v148, v112, v113
	v_cvt_pk_bf16_f32 v149, v114, v115
	ds_read_b64_tr_b16 v[88:89], v224 offset:28672
	ds_read_b64_tr_b16 v[90:91], v224 offset:29184
	v_add_f32_e32 v64, v118, v64
	v_add_f32_e32 v64, v119, v64
	v_add_f32_e32 v64, v120, v64
	v_add_f32_e32 v84, v121, v64
	s_waitcnt lgkmcnt(10)
	v_mfma_f32_32x32x16_bf16 v[64:79], v[180:183], v[156:159], v[32:47]
	v_cvt_pk_bf16_f32 v150, v116, v117
	v_cvt_pk_bf16_f32 v151, v118, v119
	ds_read_b64_tr_b16 v[80:81], v224 offset:25600
	ds_read_b64_tr_b16 v[82:83], v224 offset:26112
	s_waitcnt lgkmcnt(11)
	v_mfma_f32_32x32x16_bf16 v[96:111], v[184:187], v[152:155], v[96:111]
	v_add_f32_e32 v84, v122, v84
	v_add_f32_e32 v84, v123, v84
	v_add_f32_e32 v84, v124, v84
	v_add_f32_e32 v112, v125, v84
	v_cvt_pk_bf16_f32 v144, v120, v121
	v_cvt_pk_bf16_f32 v145, v122, v123
	ds_read_b64_tr_b16 v[84:85], v224 offset:29696
	ds_read_b64_tr_b16 v[86:87], v224 offset:30208
	s_waitcnt lgkmcnt(12)
	v_mfma_f32_32x32x16_bf16 v[64:79], v[92:95], v[152:155], v[64:79]
	v_add_f32_e32 v92, v126, v112
	v_add_f32_e32 v92, v127, v92
	v_add_f32_e32 v92, v48, v92
	v_add_f32_e32 v112, v49, v92
	v_cvt_pk_bf16_f32 v146, v124, v125
	v_cvt_pk_bf16_f32 v147, v126, v127
	ds_read_b64_tr_b16 v[92:93], v224 offset:26624
	ds_read_b64_tr_b16 v[94:95], v224 offset:27136
	s_waitcnt lgkmcnt(13)
	v_mfma_f32_32x32x16_bf16 v[96:111], v[176:179], v[140:143], v[96:111]
	v_add_f32_e32 v112, v50, v112
	v_add_f32_e32 v112, v51, v112
	v_add_f32_e32 v112, v52, v112
	v_add_f32_e32 v112, v53, v112
	v_cvt_pk_bf16_f32 v136, v48, v49
	v_cvt_pk_bf16_f32 v137, v50, v51
	ds_read_b64_tr_b16 v[48:49], v224 offset:30720
	ds_read_b64_tr_b16 v[50:51], v224 offset:31232
	s_waitcnt lgkmcnt(14)
	v_mfma_f32_32x32x16_bf16 v[64:79], v[172:175], v[140:143], v[64:79]
	v_add_f32_e32 v112, v54, v112
	v_add_f32_e32 v112, v55, v112
	v_add_f32_e32 v112, v56, v112
	v_add_f32_e32 v112, v57, v112
	v_cvt_pk_bf16_f32 v138, v52, v53
	v_cvt_pk_bf16_f32 v139, v54, v55
	ds_read_b64_tr_b16 v[52:53], v224 offset:27648
	ds_read_b64_tr_b16 v[54:55], v224 offset:28160
	s_waitcnt lgkmcnt(14)
	v_mfma_f32_32x32x16_bf16 v[96:111], v[168:171], v[132:135], v[96:111]
	v_add_f32_e32 v112, v58, v112
	v_add_f32_e32 v112, v59, v112
	v_add_f32_e32 v112, v60, v112
	v_add_f32_e32 v112, v61, v112
	v_cvt_pk_bf16_f32 v128, v56, v57
	v_cvt_pk_bf16_f32 v129, v58, v59
	ds_read_b64_tr_b16 v[56:57], v224 offset:31744
	ds_read_b64_tr_b16 v[58:59], v224 offset:32256
	v_mfma_f32_32x32x16_bf16 v[64:79], v[164:167], v[132:135], v[64:79]
	v_add_f32_e32 v112, v62, v112
	v_add_f32_e32 v112, v63, v112
	v_add_f32_e32 v112, 0, v112
	v_cvt_pk_bf16_f32 v130, v60, v61
	v_cvt_pk_bf16_f32 v131, v62, v63
	s_mov_b64 s[20:21], 0x7c000
	s_cmp_lg_u32 0, -1
	v_lshl_add_u64 v[60:61], v[202:203], 0, s[20:21]
	s_cselect_b32 s20, 0, 0
	s_add_i32 s20, s20, s38
	s_add_i32 s20, s20, 0xa000
	s_mov_b32 s21, m0
	s_mov_b32 m0, s20
	s_nop 0
	global_load_lds_dwordx4 v[60:61], off
	s_mov_b32 m0, s21
	s_cmp_lg_u32 s101, 0
	s_cbranch_scc0 .Ltailmx_2
	v_add_f32_e32 v180, v188, v112
	s_mov_b64 s[20:21], 0
	s_branch .LBB0_408
.Ltailmx_2:
	v_max_f32_e32 v60, v97, v97
	v_max_f32_e32 v61, v96, v96
	v_max_f32_e32 v60, v61, v60
	v_max3_f32 v61, v98, v99, v65
	v_max3_f32 v60, v60, v64, v66
	v_max3_f32 v60, v60, v67, v100
	v_max3_f32 v61, v61, v102, v103
	v_max3_f32 v60, v60, v101, v68
	v_max3_f32 v61, v61, v70, v71
	v_max3_f32 v60, v60, v69, v104
	v_max3_f32 v61, v61, v106, v107
	v_max3_f32 v60, v60, v105, v72
	v_max3_f32 v61, v61, v74, v75
	v_max3_f32 v60, v60, v73, v108
	v_max3_f32 v61, v61, v110, v111
	v_max3_f32 v60, v60, v109, v76
	v_max3_f32 v61, v61, v78, v79
	v_max3_f32 v60, v60, v77, v61
	v_mov_b32_e32 v61, v60
	s_nop 1
	v_permlane32_swap_b32_e32 v60, v61
	v_max_f32_e32 v61, v61, v61
	v_max_f32_e32 v60, v60, v60
	v_max_f32_e32 v60, v60, v61
	v_cmp_lt_f32_e32 vcc, s1, v60
	s_cmp_lg_u64 vcc, 0
	v_add_f32_e32 v180, v188, v112
	s_cselect_b64 s[20:21], -1, 0
	s_cbranch_vccnz .LBB0_424

.LBB0_410:
	ds_read_b64_tr_b16 v[116:117], v224 offset:32768
	ds_read_b64_tr_b16 v[118:119], v224 offset:33280
	s_waitcnt lgkmcnt(9)
	v_mfma_f32_32x32x16_bf16 v[80:95], v[60:63], v[156:159], v[32:47]
	v_add_f32_e32 v48, v96, v97
	v_add_f32_e32 v48, v98, v48
	v_add_f32_e32 v48, v99, v48
	v_add_f32_e32 v48, v100, v48
	v_add_f32_e32 v48, v101, v48
	v_cvt_pk_bf16_f32 v148, v96, v97
	v_cvt_pk_bf16_f32 v149, v98, v99
	ds_read_b64_tr_b16 v[112:113], v224 offset:36864
	ds_read_b64_tr_b16 v[114:115], v224 offset:37376
	v_add_f32_e32 v48, v102, v48
	v_add_f32_e32 v48, v103, v48
	v_add_f32_e32 v48, v104, v48
	v_add_f32_e32 v128, v105, v48
	s_waitcnt lgkmcnt(10)
	v_mfma_f32_32x32x16_bf16 v[48:63], v[172:175], v[156:159], v[32:47]
	v_cvt_pk_bf16_f32 v150, v100, v101
	v_cvt_pk_bf16_f32 v151, v102, v103
	ds_read_b64_tr_b16 v[96:97], v224 offset:33792
	ds_read_b64_tr_b16 v[98:99], v224 offset:34304
	s_waitcnt lgkmcnt(11)
	v_mfma_f32_32x32x16_bf16 v[80:95], v[176:179], v[152:155], v[80:95]
	v_add_f32_e32 v100, v106, v128
	v_add_f32_e32 v100, v107, v100
	v_add_f32_e32 v100, v108, v100
	v_add_f32_e32 v128, v109, v100
	v_cvt_pk_bf16_f32 v144, v104, v105
	v_cvt_pk_bf16_f32 v145, v106, v107
	ds_read_b64_tr_b16 v[100:101], v224 offset:37888
	ds_read_b64_tr_b16 v[102:103], v224 offset:38400
	s_waitcnt lgkmcnt(12)
	v_mfma_f32_32x32x16_bf16 v[48:63], v[168:171], v[152:155], v[48:63]
	v_add_f32_e32 v104, v110, v128
	v_add_f32_e32 v104, v111, v104
	v_add_f32_e32 v104, v64, v104
	v_add_f32_e32 v128, v65, v104
	v_cvt_pk_bf16_f32 v146, v108, v109
	v_cvt_pk_bf16_f32 v147, v110, v111
	ds_read_b64_tr_b16 v[104:105], v224 offset:34816
	ds_read_b64_tr_b16 v[106:107], v224 offset:35328
	s_waitcnt lgkmcnt(13)
	v_mfma_f32_32x32x16_bf16 v[80:95], v[164:167], v[140:143], v[80:95]
	v_add_f32_e32 v108, v66, v128
	v_add_f32_e32 v108, v67, v108
	v_add_f32_e32 v108, v68, v108
	v_add_f32_e32 v108, v69, v108
	v_cvt_pk_bf16_f32 v136, v64, v65
	v_cvt_pk_bf16_f32 v137, v66, v67
	ds_read_b64_tr_b16 v[64:65], v224 offset:38912
	ds_read_b64_tr_b16 v[66:67], v224 offset:39424
	s_waitcnt lgkmcnt(14)
	v_mfma_f32_32x32x16_bf16 v[48:63], v[160:163], v[140:143], v[48:63]
	v_add_f32_e32 v108, v70, v108
	v_add_f32_e32 v108, v71, v108
	v_add_f32_e32 v108, v72, v108
	v_add_f32_e32 v108, v73, v108
	v_cvt_pk_bf16_f32 v138, v68, v69
	v_cvt_pk_bf16_f32 v139, v70, v71
	ds_read_b64_tr_b16 v[68:69], v224 offset:35840
	ds_read_b64_tr_b16 v[70:71], v224 offset:36352
	s_waitcnt lgkmcnt(14)
	v_mfma_f32_32x32x16_bf16 v[80:95], v[124:127], v[132:135], v[80:95]
	v_add_f32_e32 v108, v74, v108
	v_add_f32_e32 v108, v75, v108
	v_add_f32_e32 v108, v76, v108
	v_add_f32_e32 v108, v77, v108
	v_cvt_pk_bf16_f32 v128, v72, v73
	v_cvt_pk_bf16_f32 v129, v74, v75
	ds_read_b64_tr_b16 v[72:73], v224 offset:39936
	ds_read_b64_tr_b16 v[74:75], v224 offset:40448
	v_mfma_f32_32x32x16_bf16 v[48:63], v[120:123], v[132:135], v[48:63]
	v_add_f32_e32 v108, v78, v108
	v_add_f32_e32 v108, v79, v108
	v_add_f32_e32 v108, 0, v108
	v_cvt_pk_bf16_f32 v130, v76, v77
	v_cvt_pk_bf16_f32 v131, v78, v79
	s_mov_b64 s[20:21], 0x7e000
	v_lshl_add_u64 v[76:77], v[202:203], 0, s[20:21]
	s_mov_b32 s20, m0
	s_mov_b32 m0, s35
	s_nop 0
	global_load_lds_dwordx4 v[76:77], off
	s_mov_b32 m0, s20
	s_cmp_lg_u32 s101, 0
	s_cbranch_scc0 .Ltailmx_3
	v_add_f32_e32 v181, v180, v108
	s_mov_b64 s[20:21], 0
	s_branch .LBB0_411
.Ltailmx_3:
	v_max_f32_e32 v76, v81, v81
	v_max_f32_e32 v77, v80, v80
	v_max_f32_e32 v76, v77, v76
	s_nop 1
	v_max3_f32 v77, v82, v83, v49
	v_max3_f32 v76, v76, v48, v50
	v_max3_f32 v76, v76, v51, v84
	v_max3_f32 v77, v77, v86, v87
	v_max3_f32 v76, v76, v85, v52
	v_max3_f32 v77, v77, v54, v55
	v_max3_f32 v76, v76, v53, v88
	v_max3_f32 v77, v77, v90, v91
	v_max3_f32 v76, v76, v89, v56
	v_max3_f32 v77, v77, v58, v59
	v_max3_f32 v76, v76, v57, v92
	v_max3_f32 v77, v77, v94, v95
	v_max3_f32 v76, v76, v93, v60
	v_max3_f32 v77, v77, v62, v63
	v_max3_f32 v76, v76, v61, v77
	v_mov_b32_e32 v77, v76
	s_nop 1
	v_permlane32_swap_b32_e32 v76, v77
	v_max_f32_e32 v77, v77, v77
	v_max_f32_e32 v76, v76, v76
	v_max_f32_e32 v76, v76, v77
	v_cmp_lt_f32_e32 vcc, s1, v76
	s_cmp_lg_u64 vcc, 0
	v_add_f32_e32 v181, v180, v108
	s_cselect_b64 s[20:21], -1, 0
	s_cbranch_vccnz .LBB0_427
